# row-norm exchange in the two fused epilogues: per-wave poll of the partial-sum slots against a -1 sentinel (no arrival counter, no store drain, no mid barrier)
# speedup vs baseline: 1.0009x; 1.0009x over previous
; #define LAS __attribute__((address_space(3)))
; __global__ void __launch_bounds__(NTHREADS, 2) fwd_megakernel(Params p) {
;     ...
;     volatile LAS unsigned* bst = (volatile LAS unsigned*)(lds + LDS_BYTES - 16);
;     const int lo = p.ph_lo, hi = p.ph_hi, G = gridDim.x, cid = blockIdx.x;
;     if (threadIdx.x < 4) bst[threadIdx.x] = 0u;
;     __syncthreads();
;     XcdBarrier bar; bar.bar = (unsigned*)(p.ws + WS_BAR); bar.x = 0; bar.st = bst; bar.G = gridDim.x;
;     if (!MK_PER_PHASE) bar = xcd_barrier_post((unsigned*)(p.ws + WS_BAR), bst, gridDim.x);
_Z14fwd_megakernel6Params:
	s_load_dwordx2 s[34:35], s[0:1], 0x90
	s_load_dwordx4 s[28:31], s[0:1], 0x80
	s_load_dword s3, s[0:1], 0xa0
	s_add_u32 s4, s0, 0xa0
	v_and_b32_e32 v170, 0x3ff, v0
	s_addc_u32 s5, s1, 0
	v_cmp_gt_u32_e32 vcc, 4, v170
	s_and_saveexec_b64 s[6:7], vcc
	v_lshl_add_u32 v1, v170, 2, 0
	v_add_u32_e32 v1, 0x24ff0, v1
	v_mov_b32_e32 v2, 0
	ds_write_b32 v1, v2
	s_or_b64 exec, exec, s[6:7]
	s_load_dwordx2 s[96:97], s[0:1], 0x98
	s_waitcnt lgkmcnt(0)
	s_cmp_lg_u32 s96, 0
	s_cbranch_scc1 .Lssq_init_skip
	s_and_b32 s98, s2, 7
	s_lshl_b32 s98, s98, 3
	s_bfe_u32 s99, s2, 0x30003
	s_or_b32 s98, s98, s99
	s_lshl_b32 s98, s98, 2
	s_lshr_b32 s99, s2, 6
	s_or_b32 s98, s98, s99
	v_and_b32_e32 v1, 0xff, v170
	v_lshl_add_u32 v1, s98, 8, v1
	v_lshlrev_b32_e32 v1, 2, v1
	v_lshrrev_b32_e32 v2, 8, v170
	v_lshl_add_u32 v1, v2, 20, v1
	v_add_u32_e32 v1, 0x100000, v1
	v_mov_b32_e32 v2, 0xbf800000
	global_store_dword v1, v2, s[34:35]
.Lssq_init_skip:
	s_add_u32 s6, s34, 0x80000
	s_addc_u32 s7, s35, 0
	v_writelane_b32 v240, s6, 0
	s_barrier
	s_nop 0
	v_writelane_b32 v240, s7, 1
	s_getreg_b32 s6, hwreg(HW_REG_XCC_ID, 0, 4)
	s_and_b32 s87, s6, 15
	s_mov_b32 s6, 0
	v_cmp_eq_u32_e64 s[58:59], 0, v170
	v_writelane_b32 v240, s6, 2
	s_and_saveexec_b64 s[6:7], s[58:59]
	s_cbranch_execz .LBB0_5
	s_mov_b64 s[8:9], exec
	v_mbcnt_lo_u32_b32 v1, s8, 0
	v_mbcnt_hi_u32_b32 v1, s9, v1
	v_cmp_eq_u32_e32 vcc, 0, v1
	s_and_b64 s[10:11], exec, vcc
	s_mov_b64 exec, s[10:11]
	s_cbranch_execz .LBB0_5
	s_bcnt1_i32_b64 s8, s[8:9]
	s_lshl_b32 s10, s87, 8
	v_mov_b32_e32 v2, s8
	v_readlane_b32 s8, v240, 0
	v_mov_b32_e32 v1, s10
	v_readlane_b32 s9, v240, 1
	s_nop 4
	global_atomic_add v1, v2, s[8:9] offset:1024

;     __device__ __forceinline__ void run(const f32x4 (&v)[2][2][4][2], const Unit& u, int wr, int wc, int fr, int fq, LAS unsigned char* lds, int wid, int lane) const {
;     ...
;         asm volatile("s_waitcnt vmcnt(0)" ::: "memory");
;         if (lane == 0) __hip_atomic_fetch_add(cnt + 64 * u.pm, 1u, __ATOMIC_RELAXED, __HIP_MEMORY_SCOPE_AGENT);
;         if (wid == 0) { unsigned sp = 0;
;             while ((unsigned)__builtin_amdgcn_readfirstlane(__hip_atomic_load(cnt + 64 * u.pm, __ATOMIC_RELAXED, __HIP_MEMORY_SCOPE_AGENT)) < 32u) { __builtin_amdgcn_s_sleep(2); if (++sp > (1u << 22)) break; }
;             __builtin_amdgcn_fence(__ATOMIC_ACQUIRE, "agent"); }
;         asm volatile("s_waitcnt vmcnt(0) lgkmcnt(0)" ::: "memory"); __builtin_amdgcn_s_barrier(); asm volatile("" ::: "memory");
;         if (lane < 32) { const float* slot = xbuf + (size_t)(u.pm * BM + row) * 4; float t = 0.f;
; #pragma unroll
;             for (int k = 0; k < 4; ++k) t += __hip_atomic_load(slot + k, __ATOMIC_RELAXED, __HIP_MEMORY_SCOPE_AGENT);
;             S[row] = 1.0f / sqrtf(t * (1.0f / DM) + EPS); }
.LBB0_603:
.LBB0_605:
.LBB0_606:
.LBB0_612:
.LBB0_613:
	s_and_saveexec_b64 s[6:7], s[0:1]
	s_cbranch_execz .LBB0_615
	v_lshl_add_u64 v[0:1], v[0:1], 4, s[12:13]
	s_movk_i32 s11, 0x4000
.Lssq_poll_a:
	global_load_dword v3, v[0:1], off sc1
	global_load_dword v128, v[0:1], off offset:4 sc1
	global_load_dword v129, v[0:1], off offset:8 sc1
	global_load_dword v236, v[0:1], off offset:12 sc1
	s_waitcnt vmcnt(0)
	v_min_f32_e32 v237, v3, v128
	v_min3_f32 v237, v237, v129, v236
	v_cmp_gt_f32_e32 vcc, 0, v237
	s_cbranch_vccz .Lssq_done_a
	s_sleep 1
	s_add_i32 s11, s11, -1
	s_cmp_lg_u32 s11, 0
	s_cbranch_scc1 .Lssq_poll_a
.Lssq_done_a:
	v_mov_b32_e32 v0, v236
	v_mov_b32_e32 v1, 0x358637bd
	s_mov_b32 s0, 0xf800000
	v_add_f32_e32 v3, 0, v3
	v_add_f32_e32 v3, v3, v128
	v_add_f32_e32 v3, v3, v129
	v_add_f32_e32 v0, v3, v0
	v_fmac_f32_e32 v1, 0x3a800000, v0
	v_mul_f32_e32 v0, 0x4f800000, v1
	v_cmp_gt_f32_e32 vcc, s0, v1
	v_mov_b32_e32 v3, 0x260
	s_nop 0
	v_cndmask_b32_e32 v0, v1, v0, vcc
	v_sqrt_f32_e32 v1, v0
	s_nop 0
	v_add_u32_e32 v128, -1, v1
	v_add_u32_e32 v129, 1, v1
	v_fma_f32 v130, -v128, v1, v0
	v_fma_f32 v131, -v129, v1, v0
	v_cmp_ge_f32_e64 s[0:1], 0, v130
	s_nop 1
	v_cndmask_b32_e64 v1, v1, v128, s[0:1]
	v_cmp_lt_f32_e64 s[0:1], 0, v131
	s_nop 1
	v_cndmask_b32_e64 v1, v1, v129, s[0:1]
	v_mul_f32_e32 v128, 0x37800000, v1
	v_cndmask_b32_e32 v1, v1, v128, vcc
	v_cmp_class_f32_e32 vcc, v0, v3
	s_nop 1
	v_cndmask_b32_e32 v0, v1, v0, vcc
	v_div_scale_f32 v1, s[0:1], v0, v0, 1.0
	v_rcp_f32_e32 v3, v1
	v_div_scale_f32 v128, vcc, 1.0, v0, 1.0
	v_fma_f32 v129, -v1, v3, 1.0
	v_fmac_f32_e32 v3, v129, v3
	v_mul_f32_e32 v129, v128, v3
	v_fma_f32 v130, -v1, v129, v128
	v_fmac_f32_e32 v129, v130, v3
	v_fma_f32 v1, -v1, v129, v128
	v_div_fmas_f32 v1, v1, v3, v129
	v_div_fixup_f32 v0, v1, v0, 1.0
	v_lshl_add_u32 v1, v2, 2, 0
	ds_write_b32 v1, v0 offset:4096

;     __device__ __forceinline__ void run(const f32x4 (&v)[2][2][4][2], const Unit& u, int wr, int wc, int fr, int fq, LAS unsigned char* lds, int wid, int lane) const {
;     ...
;         asm volatile("s_waitcnt vmcnt(0)" ::: "memory");
;         if (lane == 0) __hip_atomic_fetch_add(cnt + 64 * u.pm, 1u, __ATOMIC_RELAXED, __HIP_MEMORY_SCOPE_AGENT);
;         if (wid == 0) { unsigned sp = 0;
;             while ((unsigned)__builtin_amdgcn_readfirstlane(__hip_atomic_load(cnt + 64 * u.pm, __ATOMIC_RELAXED, __HIP_MEMORY_SCOPE_AGENT)) < 32u) { __builtin_amdgcn_s_sleep(2); if (++sp > (1u << 22)) break; }
;             __builtin_amdgcn_fence(__ATOMIC_ACQUIRE, "agent"); }
;         asm volatile("s_waitcnt vmcnt(0) lgkmcnt(0)" ::: "memory"); __builtin_amdgcn_s_barrier(); asm volatile("" ::: "memory");
;         if (lane < 32) { const float* slot = xbuf + (size_t)(u.pm * BM + row) * 4; float t = 0.f;
; #pragma unroll
;             for (int k = 0; k < 4; ++k) t += __hip_atomic_load(slot + k, __ATOMIC_RELAXED, __HIP_MEMORY_SCOPE_AGENT);
;             S[row] = 1.0f / sqrtf(t * (1.0f / DM) + EPS); }
.LBB0_1146:
.LBB0_1148:
.LBB0_1149:
.LBB0_1155:
.LBB0_1156:
	s_and_saveexec_b64 s[8:9], s[0:1]
	s_cbranch_execz .LBB0_1158
	v_lshl_add_u64 v[128:129], v[128:129], 4, s[6:7]
	s_movk_i32 s11, 0x4000
.Lssq_poll_b:
	global_load_dword v131, v[128:129], off sc1
	global_load_dword v132, v[128:129], off offset:4 sc1
	global_load_dword v133, v[128:129], off offset:8 sc1
	global_load_dword v236, v[128:129], off offset:12 sc1
	s_waitcnt vmcnt(0)
	v_min_f32_e32 v237, v131, v132
	v_min3_f32 v237, v237, v133, v236
	v_cmp_gt_f32_e32 vcc, 0, v237
	s_cbranch_vccz .Lssq_done_b
	s_sleep 1
	s_add_i32 s11, s11, -1
	s_cmp_lg_u32 s11, 0
	s_cbranch_scc1 .Lssq_poll_b
.Lssq_done_b:
	v_mov_b32_e32 v128, v236
	v_mov_b32_e32 v129, 0x358637bd
	s_mov_b32 s0, 0xf800000
	v_add_f32_e32 v131, 0, v131
	v_add_f32_e32 v131, v131, v132
	v_add_f32_e32 v131, v131, v133
	v_add_f32_e32 v128, v131, v128
	v_fmac_f32_e32 v129, 0x3a800000, v128
	v_mul_f32_e32 v128, 0x4f800000, v129
	v_cmp_gt_f32_e32 vcc, s0, v129
	v_mov_b32_e32 v131, 0x260
	s_nop 0
	v_cndmask_b32_e32 v128, v129, v128, vcc
	v_sqrt_f32_e32 v129, v128
	s_nop 0
	v_add_u32_e32 v132, -1, v129
	v_add_u32_e32 v133, 1, v129
	v_fma_f32 v134, -v132, v129, v128
	v_fma_f32 v135, -v133, v129, v128
	v_cmp_ge_f32_e64 s[0:1], 0, v134
	s_nop 1
	v_cndmask_b32_e64 v129, v129, v132, s[0:1]
	v_cmp_lt_f32_e64 s[0:1], 0, v135
	s_nop 1
	v_cndmask_b32_e64 v129, v129, v133, s[0:1]
	v_mul_f32_e32 v132, 0x37800000, v129
	v_cndmask_b32_e32 v129, v129, v132, vcc
	v_cmp_class_f32_e32 vcc, v128, v131
	s_nop 1
	v_cndmask_b32_e32 v128, v129, v128, vcc
	v_div_scale_f32 v129, s[0:1], v128, v128, 1.0
	v_rcp_f32_e32 v131, v129
	v_div_scale_f32 v132, vcc, 1.0, v128, 1.0
	v_fma_f32 v133, -v129, v131, 1.0
	v_fmac_f32_e32 v131, v133, v131
	v_mul_f32_e32 v133, v132, v131
	v_fma_f32 v134, -v129, v133, v132
	v_fmac_f32_e32 v133, v134, v131
	v_fma_f32 v129, -v129, v133, v132
	v_div_fmas_f32 v129, v129, v131, v133
	v_div_fixup_f32 v128, v129, v128, 1.0
	v_lshl_add_u32 v129, v130, 2, 0
	ds_write_b32 v129, v128 offset:4096
